# P2 tail weight conversion split: workgroups 128-255 take items below 0x4000, workgroups 0-127 the rest after their ninth unit
# baseline (speedup 1.0000x reference)
.LBB0_483:
	s_cmpk_lg_u32 s95, 0x100
	s_cbranch_scc1 .Lconv_orig
	s_and_b32 s1, s81, 0x7f
	s_lshl_b32 s2, s1, 3
	s_ashr_i32 s1, s20, 6
	s_add_i32 s2, s1, s2
	s_movk_i32 s0, 0x80
	s_movk_i32 s99, 0x4000
	s_cmpk_lt_u32 s81, 0x80
	s_cbranch_scc0 .Lconv_go
	s_addk_i32 s2, 0x4000
	s_movk_i32 s99, 0x4c00
